# grid sync counter moved from runtime sync buffer into d_ws ctl word 0 (same cg algorithm), 8 in-loop sites
# speedup vs baseline: 1.0178x; 1.0178x over previous
; __global__ void __launch_bounds__(512) mega(Params P) {
;   cg::grid_group grid = cg::this_grid();
;   unsigned char* ws = P.ws;
;   if (EN & 1) prologue(P);
;   grid.sync();
.LBB0_225:
	s_or_b64 exec, exec, s[4:5]
	s_barrier
	s_mov_b64 s[2:3], exec
	v_readlane_b32 s0, v253, 57
	v_readlane_b32 s1, v253, 58
	s_and_b64 s[0:1], s[2:3], s[0:1]
	s_mov_b64 exec, s[0:1]
	s_cbranch_execz .LBB0_235
	buffer_wbl2 sc1
	s_waitcnt vmcnt(0)
	s_load_dwordx2 s[4:5], s[56:57], -0x8
	s_load_dword s0, s[56:57], 0x0
	s_mov_b64 s[6:7], exec
	v_mbcnt_lo_u32_b32 v2, s6, 0
	v_mbcnt_hi_u32_b32 v2, s7, v2
	v_cmp_eq_u32_e32 vcc, 0, v2
	s_waitcnt lgkmcnt(0)
	v_mov_b32_e32 v0, s0
	s_and_saveexec_b64 s[8:9], vcc
	s_cbranch_execz .LBB0_228
	s_bcnt1_i32_b64 s0, s[6:7]
	v_mov_b32_e32 v3, s0
	global_atomic_add v3, v1, v3, s[4:5] sc0
.LBB0_228:
	s_or_b64 exec, exec, s[8:9]
	s_waitcnt vmcnt(0)
	v_readfirstlane_b32 s0, v3
	v_add_u32_e32 v3, -1, v0
	s_nop 0
	v_add_u32_e32 v2, s0, v2
	v_cmp_eq_u32_sdwa s[0:1], v2, v3 src0_sel:WORD_0 src1_sel:DWORD
	s_and_saveexec_b64 s[6:7], s[0:1]
	s_cbranch_execz .LBB0_231
	s_mov_b64 s[8:9], exec
	v_mbcnt_lo_u32_b32 v3, s8, 0
	v_mbcnt_hi_u32_b32 v3, s9, v3
	v_cmp_eq_u32_e32 vcc, 0, v3
	s_and_b64 s[0:1], exec, vcc
	s_mov_b64 exec, s[0:1]
	s_cbranch_execz .LBB0_231
	v_sub_u32_e32 v0, 0x10000, v0
	s_bcnt1_i32_b64 s0, s[8:9]
	v_mul_lo_u32 v0, v0, s0
	global_atomic_add v1, v0, s[4:5]
.LBB0_231:
	s_or_b64 exec, exec, s[6:7]
	global_load_dword v3, v1, s[4:5] sc1
	v_and_b32_e32 v0, 0xffff0000, v2
	s_waitcnt vmcnt(0)
	v_and_b32_e32 v2, 0xffff0000, v3
	v_cmp_eq_u32_e32 vcc, v2, v0
	s_and_b64 exec, exec, vcc
	s_cbranch_execz .LBB0_234
	s_mov_b64 s[6:7], 0
.LBB0_233:
	s_sleep 1
	global_load_dword v2, v1, s[4:5] sc1
	s_waitcnt vmcnt(0)
	v_and_b32_e32 v2, 0xffff0000, v2
	v_cmp_ne_u32_e32 vcc, v2, v0
	s_or_b64 s[6:7], vcc, s[6:7]
	s_andn2_b64 exec, exec, s[6:7]
	s_cbranch_execnz .LBB0_233

; __global__ void __launch_bounds__(512) mega(Params P) {
;     ...
;       if (EN & 2) gemm_phase(HN, DM, (const bf16_t*)(ws + WS_WIN) + (size_t)l * N_IN * 1024, 1024, NREAL, N_IN, 1024, e); }
;     grid.sync();
.LBB0_769:
	s_waitcnt vmcnt(0) lgkmcnt(0)
	s_barrier
	s_mov_b64 s[2:3], exec
	v_readlane_b32 s0, v253, 57
	v_readlane_b32 s1, v253, 58
	s_and_b64 s[0:1], s[2:3], s[0:1]
	s_mov_b64 exec, s[0:1]
	s_cbranch_execz .LBB0_779
	buffer_wbl2 sc1
	s_waitcnt vmcnt(0)
	s_load_dwordx2 s[4:5], s[56:57], -0x8
	s_load_dword s0, s[56:57], 0x0
	s_mov_b64 s[6:7], exec
	v_mbcnt_lo_u32_b32 v2, s6, 0
	v_mbcnt_hi_u32_b32 v2, s7, v2
	v_cmp_eq_u32_e32 vcc, 0, v2
	s_waitcnt lgkmcnt(0)
	v_mov_b32_e32 v0, s0
	s_and_saveexec_b64 s[8:9], vcc
	s_cbranch_execz .LBB0_772
	s_bcnt1_i32_b64 s0, s[6:7]
	v_mov_b32_e32 v3, s0
	global_atomic_add v3, v1, v3, s[4:5] sc0

; __global__ void __launch_bounds__(512) mega(Params P) {
;     ...
;       if (EN & 4) up_phase(CQKV, (const bf16_t*)(ws + WS_WQB) + (size_t)l * 768 * 256, (const bf16_t*)(ws + WS_WKVB) + (size_t)l * 768 * 256, e); }
;     grid.sync();
.LBB0_1207:
	s_barrier
	s_mov_b64 s[2:3], exec
	v_readlane_b32 s0, v253, 57
	v_readlane_b32 s1, v253, 58
	s_and_b64 s[0:1], s[2:3], s[0:1]
	s_mov_b64 exec, s[0:1]
	s_cbranch_execz .LBB0_1217
	buffer_wbl2 sc1
	s_waitcnt vmcnt(0)
	s_load_dwordx2 s[4:5], s[56:57], -0x8
	s_load_dword s0, s[56:57], 0x0
	s_mov_b64 s[6:7], exec
	v_mbcnt_lo_u32_b32 v2, s6, 0
	v_mbcnt_hi_u32_b32 v2, s7, v2
	v_cmp_eq_u32_e32 vcc, 0, v2
	s_waitcnt lgkmcnt(0)
	v_mov_b32_e32 v0, s0
	s_and_saveexec_b64 s[8:9], vcc
	s_cbranch_execz .LBB0_1210
	s_bcnt1_i32_b64 s0, s[6:7]
	v_mov_b32_e32 v3, s0
	global_atomic_add v3, v1, v3, s[4:5] sc0

; __global__ void __launch_bounds__(512) mega(Params P) {
;     ...
;     attn_phase(P, l);
;     grid.sync();
.LBB0_1432:
	s_waitcnt lgkmcnt(0)
	s_barrier
	s_mov_b64 s[2:3], exec
	v_readlane_b32 s0, v253, 57
	v_readlane_b32 s1, v253, 58
	v_readlane_b32 s56, v254, 50
	s_and_b64 s[0:1], s[2:3], s[0:1]
	v_readlane_b32 s52, v254, 52
	v_readlane_b32 s57, v254, 51
	v_readlane_b32 s53, v254, 53
	s_mov_b64 exec, s[0:1]
	s_cbranch_execz .LBB0_1442
	buffer_wbl2 sc1
	s_waitcnt vmcnt(0)
	s_load_dwordx2 s[4:5], s[56:57], -0x8
	s_load_dword s0, s[56:57], 0x0
	s_mov_b64 s[6:7], exec
	v_mbcnt_lo_u32_b32 v2, s6, 0
	v_mbcnt_hi_u32_b32 v2, s7, v2
	v_cmp_eq_u32_e32 vcc, 0, v2
	s_waitcnt lgkmcnt(0)
	v_mov_b32_e32 v0, s0
	s_and_saveexec_b64 s[8:9], vcc
	s_cbranch_execz .LBB0_1435
	s_bcnt1_i32_b64 s0, s[6:7]
	v_mov_b32_e32 v3, s0
	global_atomic_add v3, v1, v3, s[4:5] sc0

; __global__ void __launch_bounds__(512) mega(Params P) {
;     ...
;     else { EpiResid e; e.H = H; gemm_phase(HN, DM, (const bf16_t*)(ws + WS_WOUT) + (size_t)l * 1024 * 1024, 1024, NREAL, 1024, 1024, e); }
;     grid.sync();
.LBB0_1489:
	s_waitcnt lgkmcnt(0)
	s_barrier
	s_mov_b64 s[4:5], exec
	v_readlane_b32 s0, v253, 57
	v_readlane_b32 s1, v253, 58
	s_and_b64 s[0:1], s[4:5], s[0:1]
	s_mov_b64 exec, s[0:1]
	s_cbranch_execz .LBB0_1499
	buffer_wbl2 sc1
	s_waitcnt vmcnt(0)
	s_load_dwordx2 s[6:7], s[56:57], -0x8
	s_load_dword s0, s[56:57], 0x0
	s_mov_b64 s[8:9], exec
	v_mbcnt_lo_u32_b32 v2, s8, 0
	v_mbcnt_hi_u32_b32 v2, s9, v2
	v_cmp_eq_u32_e32 vcc, 0, v2
	s_waitcnt lgkmcnt(0)
	v_mov_b32_e32 v0, s0
	s_and_saveexec_b64 s[10:11], vcc
	s_cbranch_execz .LBB0_1492
	s_bcnt1_i32_b64 s0, s[8:9]
	v_mov_b32_e32 v3, s0
	global_atomic_add v3, v1, v3, s[6:7] sc0
.LBB0_1492:
	s_or_b64 exec, exec, s[10:11]
	s_waitcnt vmcnt(0)
	v_readfirstlane_b32 s0, v3
	v_add_u32_e32 v3, -1, v0
	s_nop 0
	v_add_u32_e32 v2, s0, v2
	v_cmp_eq_u32_sdwa s[0:1], v2, v3 src0_sel:WORD_0 src1_sel:DWORD
	s_and_saveexec_b64 s[8:9], s[0:1]
	s_cbranch_execz .LBB0_1495
	s_mov_b64 s[10:11], exec
	v_mbcnt_lo_u32_b32 v3, s10, 0
	v_mbcnt_hi_u32_b32 v3, s11, v3
	v_cmp_eq_u32_e32 vcc, 0, v3
	s_and_b64 s[0:1], exec, vcc
	s_mov_b64 exec, s[0:1]
	s_cbranch_execz .LBB0_1495
	v_sub_u32_e32 v0, 0x10000, v0
	s_bcnt1_i32_b64 s0, s[10:11]
	v_mul_lo_u32 v0, v0, s0
	global_atomic_add v1, v0, s[6:7]
.LBB0_1495:
	s_or_b64 exec, exec, s[8:9]
	global_load_dword v3, v1, s[6:7] sc1
	v_and_b32_e32 v0, 0xffff0000, v2
	s_waitcnt vmcnt(0)
	v_and_b32_e32 v2, 0xffff0000, v3
	v_cmp_eq_u32_e32 vcc, v2, v0
	s_and_b64 exec, exec, vcc
	s_cbranch_execz .LBB0_1498
	s_mov_b64 s[8:9], 0
.LBB0_1497:
	s_sleep 1
	global_load_dword v2, v1, s[6:7] sc1
	s_waitcnt vmcnt(0)
	v_and_b32_e32 v2, 0xffff0000, v2
	v_cmp_ne_u32_e32 vcc, v2, v0
	s_or_b64 s[8:9], vcc, s[8:9]
	s_andn2_b64 exec, exec, s[8:9]
	s_cbranch_execnz .LBB0_1497

; __global__ void __launch_bounds__(512) mega(Params P) {
;     ...
;     norm_phase(H, P.ffn_norm + l * DM, HN);
;     grid.sync();
.LBB0_1502:
	s_or_b64 exec, exec, s[6:7]
	s_barrier
	s_mov_b64 s[4:5], exec
	v_readlane_b32 s0, v253, 57
	v_readlane_b32 s1, v253, 58
	s_and_b64 s[0:1], s[4:5], s[0:1]
	s_mov_b64 exec, s[0:1]
	s_cbranch_execz .LBB0_1512
	buffer_wbl2 sc1
	s_waitcnt vmcnt(0)
	s_load_dwordx2 s[6:7], s[56:57], -0x8
	s_load_dword s0, s[56:57], 0x0
	s_mov_b64 s[8:9], exec
	v_mbcnt_lo_u32_b32 v2, s8, 0
	v_mbcnt_hi_u32_b32 v2, s9, v2
	v_cmp_eq_u32_e32 vcc, 0, v2
	s_waitcnt lgkmcnt(0)
	v_mov_b32_e32 v0, s0
	s_and_saveexec_b64 s[10:11], vcc
	s_cbranch_execz .LBB0_1505
	s_bcnt1_i32_b64 s0, s[8:9]
	v_mov_b32_e32 v3, s0
	global_atomic_add v3, v1, v3, s[6:7] sc0

; __global__ void __launch_bounds__(512) mega(Params P) {
;     ...
;     if (EN & 128) { EpiGU e; e.act = (bf16_t*)(ws + WS_ACT); gemm_phase(HN, DM, (const bf16_t*)(ws + WS_WGU) + (size_t)l * N_GU * 1024, 1024, NREAL, N_GU, 1024, e); }
;     grid.sync();
.LBB0_1534:
	s_waitcnt vmcnt(0) lgkmcnt(0)
	s_barrier
	s_mov_b64 s[4:5], exec
	v_readlane_b32 s0, v253, 57
	v_readlane_b32 s1, v253, 58
	s_and_b64 s[0:1], s[4:5], s[0:1]
	s_mov_b64 exec, s[0:1]
	s_cbranch_execz .LBB0_1544
	buffer_wbl2 sc1
	s_waitcnt vmcnt(0)
	s_load_dwordx2 s[6:7], s[56:57], -0x8
	s_load_dword s0, s[56:57], 0x0
	s_mov_b64 s[8:9], exec
	v_mbcnt_lo_u32_b32 v2, s8, 0
	v_mbcnt_hi_u32_b32 v2, s9, v2
	v_cmp_eq_u32_e32 vcc, 0, v2
	s_waitcnt lgkmcnt(0)
	v_mov_b32_e32 v0, s0
	s_and_saveexec_b64 s[10:11], vcc
	s_cbranch_execz .LBB0_1537
	s_bcnt1_i32_b64 s0, s[8:9]
	v_mov_b32_e32 v3, s0
	global_atomic_add v3, v1, v3, s[6:7] sc0

; __global__ void __launch_bounds__(512) mega(Params P) {
;     ...
;     if (EN & 256) { EpiResid e; e.H = H; gemm_phase((const bf16_t*)(ws + WS_ACT), DFF, (const bf16_t*)(ws + WS_WDN) + (size_t)l * 1024 * DFF, DFF, NREAL, 1024, DFF, e); }
;     grid.sync();
.LBB0_1567:
	buffer_wbl2 sc1
	s_waitcnt vmcnt(0)
	s_load_dwordx2 s[4:5], s[56:57], -0x8
	s_load_dword s0, s[56:57], 0x0
	s_mov_b64 s[6:7], exec
	v_mbcnt_lo_u32_b32 v2, s6, 0
	v_mbcnt_hi_u32_b32 v2, s7, v2
	v_cmp_eq_u32_e32 vcc, 0, v2
	s_waitcnt lgkmcnt(0)
	v_mov_b32_e32 v0, s0
	s_and_saveexec_b64 s[8:9], vcc
	s_cbranch_execz .LBB0_1569
	s_bcnt1_i32_b64 s0, s[6:7]
	v_mov_b32_e32 v3, s0
	global_atomic_add v3, v1, v3, s[4:5] sc0

; __global__ void __launch_bounds__(512) mega(Params P) {
;     ...
;     if (EN & 256) { EpiResid e; e.H = H; gemm_phase((const bf16_t*)(ws + WS_ACT), DFF, (const bf16_t*)(ws + WS_WDN) + (size_t)l * 1024 * DFF, DFF, NREAL, 1024, DFF, e); }
;     grid.sync();
.LBB0_1572:
	s_or_b64 exec, exec, s[6:7]
	global_load_dword v3, v1, s[4:5] sc1
	v_and_b32_e32 v0, 0xffff0000, v2
	s_waitcnt vmcnt(0)
	v_and_b32_e32 v2, 0xffff0000, v3
	v_cmp_eq_u32_e32 vcc, v2, v0
	s_and_b64 exec, exec, vcc
	s_cbranch_execnz .LBB0_1573
	s_getpc_b64 s[98:99]

; __global__ void __launch_bounds__(512) mega(Params P) {
;     ...
;     if (EN & 256) { EpiResid e; e.H = H; gemm_phase((const bf16_t*)(ws + WS_ACT), DFF, (const bf16_t*)(ws + WS_WDN) + (size_t)l * 1024 * DFF, DFF, NREAL, 1024, DFF, e); }
;     grid.sync();
.LBB0_1574:
	s_sleep 1
	global_load_dword v2, v1, s[4:5] sc1
	s_waitcnt vmcnt(0)
	v_and_b32_e32 v2, 0xffff0000, v2
	v_cmp_ne_u32_e32 vcc, v2, v0
	s_or_b64 s[6:7], vcc, s[6:7]
	s_andn2_b64 exec, exec, s[6:7]
	s_cbranch_execnz .LBB0_1574
	s_getpc_b64 s[98:99]
